# v7 + flattened grid-barrier release: non-leader workgroups poll the cross-XCD TOPGEN word directly instead of their XCD's XGEN word (one hop less per barrier)
# speedup vs baseline: 1.0135x; 1.0135x over previous
.LBB0_60:
	s_or_b64 exec, exec, s[8:9]
	v_cvt_f32_u32_e32 v5, v3
	s_waitcnt vmcnt(0)
	v_readfirstlane_b32 s6, v4
	v_sub_u32_e32 v4, 0, v3
	v_rcp_iflag_f32_e32 v5, v5
	v_add_u32_e32 v6, s6, v2
	v_mul_f32_e32 v5, 0x4f7ffffe, v5
	v_cvt_u32_f32_e32 v5, v5
	v_mul_lo_u32 v2, v4, v5
	v_mul_hi_u32 v2, v5, v2
	v_add_u32_e32 v2, v5, v2
	v_mul_hi_u32 v2, v6, v2
	v_mul_lo_u32 v4, v2, v3
	v_sub_u32_e32 v4, v6, v4
	v_add_u32_e32 v5, 1, v2
	v_cmp_ge_u32_e32 vcc, v4, v3
	s_nop 1
	v_cndmask_b32_e32 v2, v2, v5, vcc
	v_sub_u32_e32 v5, v4, v3
	v_cndmask_b32_e32 v4, v4, v5, vcc
	v_add_u32_e32 v5, 1, v2
	v_cmp_ge_u32_e32 vcc, v4, v3
	v_add_u32_e32 v4, 1, v6
	s_nop 0
	v_cndmask_b32_e32 v2, v2, v5, vcc
	v_mul_lo_u32 v5, v3, v2
	v_add_u32_e32 v3, v5, v3
	v_cmp_ne_u32_e32 vcc, v4, v3
	s_and_saveexec_b64 s[6:7], vcc
	s_xor_b64 s[6:7], exec, s[6:7]
	s_cbranch_execz .LBB0_74
	s_waitcnt lgkmcnt(0)
	v_mov_b32_e32 v1, 0x3500
	global_load_dword v1, v1, s[96:97] sc1
	s_add_u32 s10, s96, 0x3500
	s_addc_u32 s11, s97, 0
	s_waitcnt vmcnt(0)
	v_cmp_eq_u32_e32 vcc, v1, v2
	s_and_saveexec_b64 s[8:9], vcc
	s_cbranch_execz .LBB0_73
	s_mov_b32 s22, 1
	s_mov_b64 s[12:13], 0
	v_mov_b32_e32 v1, 0
	s_branch .LBB0_64

.LBB0_491:
	s_or_b64 exec, exec, s[12:13]
	v_cvt_f32_u32_e32 v5, v3
	s_waitcnt vmcnt(0)
	v_readfirstlane_b32 s10, v4
	v_sub_u32_e32 v4, 0, v3
	v_rcp_iflag_f32_e32 v5, v5
	v_add_u32_e32 v6, s10, v2
	v_mul_f32_e32 v5, 0x4f7ffffe, v5
	v_cvt_u32_f32_e32 v5, v5
	v_mul_lo_u32 v2, v4, v5
	v_mul_hi_u32 v2, v5, v2
	v_add_u32_e32 v2, v5, v2
	v_mul_hi_u32 v2, v6, v2
	v_mul_lo_u32 v4, v2, v3
	v_sub_u32_e32 v4, v6, v4
	v_add_u32_e32 v5, 1, v2
	v_cmp_ge_u32_e32 vcc, v4, v3
	s_nop 1
	v_cndmask_b32_e32 v2, v2, v5, vcc
	v_sub_u32_e32 v5, v4, v3
	v_cndmask_b32_e32 v4, v4, v5, vcc
	v_add_u32_e32 v5, 1, v2
	v_cmp_ge_u32_e32 vcc, v4, v3
	v_add_u32_e32 v4, 1, v6
	s_nop 0
	v_cndmask_b32_e32 v2, v2, v5, vcc
	v_mul_lo_u32 v5, v3, v2
	v_add_u32_e32 v3, v5, v3
	v_cmp_ne_u32_e32 vcc, v4, v3
	s_and_saveexec_b64 s[10:11], vcc
	s_xor_b64 s[10:11], exec, s[10:11]
	s_cbranch_execz .LBB0_505
	s_waitcnt lgkmcnt(0)
	v_mov_b32_e32 v1, 0x3500
	global_load_dword v1, v1, s[96:97] sc1
	s_add_u32 s14, s96, 0x3500
	s_addc_u32 s15, s97, 0
	s_waitcnt vmcnt(0)
	v_cmp_eq_u32_e32 vcc, v1, v2
	s_and_saveexec_b64 s[12:13], vcc
	s_cbranch_execz .LBB0_504
	s_mov_b32 s26, 1
	s_mov_b64 s[16:17], 0
	v_mov_b32_e32 v1, 0
	s_branch .LBB0_495

.LBB0_641:
	s_or_b64 exec, exec, s[10:11]
	v_cvt_f32_u32_e32 v5, v3
	s_waitcnt vmcnt(0)
	v_readfirstlane_b32 s6, v4
	v_sub_u32_e32 v4, 0, v3
	v_rcp_iflag_f32_e32 v5, v5
	v_add_u32_e32 v6, s6, v2
	v_mul_f32_e32 v5, 0x4f7ffffe, v5
	v_cvt_u32_f32_e32 v5, v5
	v_mul_lo_u32 v2, v4, v5
	v_mul_hi_u32 v2, v5, v2
	v_add_u32_e32 v2, v5, v2
	v_mul_hi_u32 v2, v6, v2
	v_mul_lo_u32 v4, v2, v3
	v_sub_u32_e32 v4, v6, v4
	v_add_u32_e32 v5, 1, v2
	v_cmp_ge_u32_e32 vcc, v4, v3
	s_nop 1
	v_cndmask_b32_e32 v2, v2, v5, vcc
	v_sub_u32_e32 v5, v4, v3
	v_cndmask_b32_e32 v4, v4, v5, vcc
	v_add_u32_e32 v5, 1, v2
	v_cmp_ge_u32_e32 vcc, v4, v3
	v_add_u32_e32 v4, 1, v6
	s_nop 0
	v_cndmask_b32_e32 v2, v2, v5, vcc
	v_mul_lo_u32 v5, v3, v2
	v_add_u32_e32 v3, v5, v3
	v_cmp_ne_u32_e32 vcc, v4, v3
	s_and_saveexec_b64 s[6:7], vcc
	s_xor_b64 s[6:7], exec, s[6:7]
	s_cbranch_execz .LBB0_655
	s_waitcnt lgkmcnt(0)
	v_mov_b32_e32 v1, 0x3500
	global_load_dword v1, v1, s[96:97] sc1
	s_add_u32 s12, s96, 0x3500
	s_addc_u32 s13, s97, 0
	s_waitcnt vmcnt(0)
	v_cmp_eq_u32_e32 vcc, v1, v2
	s_and_saveexec_b64 s[10:11], vcc
	s_cbranch_execz .LBB0_654
	s_mov_b32 s24, 1
	s_mov_b64 s[14:15], 0
	v_mov_b32_e32 v1, 0
	s_branch .LBB0_645

.LBB0_895:
	s_or_b64 exec, exec, s[10:11]
	v_cvt_f32_u32_e32 v6, v4
	s_waitcnt vmcnt(0)
	v_readfirstlane_b32 s6, v5
	v_sub_u32_e32 v5, 0, v4
	v_rcp_iflag_f32_e32 v6, v6
	v_add_u32_e32 v7, s6, v3
	v_mul_f32_e32 v6, 0x4f7ffffe, v6
	v_cvt_u32_f32_e32 v6, v6
	v_mul_lo_u32 v3, v5, v6
	v_mul_hi_u32 v3, v6, v3
	v_add_u32_e32 v3, v6, v3
	v_mul_hi_u32 v3, v7, v3
	v_mul_lo_u32 v5, v3, v4
	v_sub_u32_e32 v5, v7, v5
	v_add_u32_e32 v6, 1, v3
	v_cmp_ge_u32_e32 vcc, v5, v4
	s_nop 1
	v_cndmask_b32_e32 v3, v3, v6, vcc
	v_sub_u32_e32 v6, v5, v4
	v_cndmask_b32_e32 v5, v5, v6, vcc
	v_add_u32_e32 v6, 1, v3
	v_cmp_ge_u32_e32 vcc, v5, v4
	v_add_u32_e32 v5, 1, v7
	s_nop 0
	v_cndmask_b32_e32 v3, v3, v6, vcc
	v_mul_lo_u32 v6, v4, v3
	v_add_u32_e32 v4, v6, v4
	v_cmp_ne_u32_e32 vcc, v5, v4
	s_and_saveexec_b64 s[6:7], vcc
	s_xor_b64 s[6:7], exec, s[6:7]
	s_cbranch_execz .LBB0_909
	s_waitcnt lgkmcnt(0)
	v_mov_b32_e32 v2, 0x3500
	global_load_dword v2, v2, s[96:97] sc1
	s_add_u32 s12, s96, 0x3500
	s_addc_u32 s13, s97, 0
	s_waitcnt vmcnt(0)
	v_cmp_eq_u32_e32 vcc, v2, v3
	s_and_saveexec_b64 s[10:11], vcc
	s_cbranch_execz .LBB0_908
	s_mov_b32 s24, 1
	s_mov_b64 s[14:15], 0
	v_mov_b32_e32 v2, 0
	s_branch .LBB0_899

.LBB0_952:
	s_or_b64 exec, exec, s[6:7]
	v_cvt_f32_u32_e32 v6, v4
	s_waitcnt vmcnt(0)
	v_readfirstlane_b32 s4, v5
	v_sub_u32_e32 v5, 0, v4
	v_rcp_iflag_f32_e32 v6, v6
	v_add_u32_e32 v7, s4, v3
	v_mul_f32_e32 v6, 0x4f7ffffe, v6
	v_cvt_u32_f32_e32 v6, v6
	v_mul_lo_u32 v3, v5, v6
	v_mul_hi_u32 v3, v6, v3
	v_add_u32_e32 v3, v6, v3
	v_mul_hi_u32 v3, v7, v3
	v_mul_lo_u32 v5, v3, v4
	v_sub_u32_e32 v5, v7, v5
	v_add_u32_e32 v6, 1, v3
	v_cmp_ge_u32_e32 vcc, v5, v4
	s_nop 1
	v_cndmask_b32_e32 v3, v3, v6, vcc
	v_sub_u32_e32 v6, v5, v4
	v_cndmask_b32_e32 v5, v5, v6, vcc
	v_add_u32_e32 v6, 1, v3
	v_cmp_ge_u32_e32 vcc, v5, v4
	v_add_u32_e32 v5, 1, v7
	s_nop 0
	v_cndmask_b32_e32 v3, v3, v6, vcc
	v_mul_lo_u32 v6, v4, v3
	v_add_u32_e32 v4, v6, v4
	v_cmp_ne_u32_e32 vcc, v5, v4
	s_and_saveexec_b64 s[4:5], vcc
	s_xor_b64 s[4:5], exec, s[4:5]
	s_cbranch_execz .LBB0_966
	s_waitcnt lgkmcnt(0)
	v_mov_b32_e32 v2, 0x3500
	global_load_dword v2, v2, s[96:97] sc1
	s_add_u32 s12, s96, 0x3500
	s_addc_u32 s13, s97, 0
	s_waitcnt vmcnt(0)
	v_cmp_eq_u32_e32 vcc, v2, v3
	s_and_saveexec_b64 s[6:7], vcc
	s_cbranch_execz .LBB0_965
	s_mov_b32 s24, 1
	s_mov_b64 s[14:15], 0
	v_mov_b32_e32 v2, 0
	s_branch .LBB0_956

.LBB0_1037:
	s_or_b64 exec, exec, s[10:11]
	v_cvt_f32_u32_e32 v6, v4
	s_waitcnt vmcnt(0)
	v_readfirstlane_b32 s8, v5
	v_sub_u32_e32 v5, 0, v4
	v_rcp_iflag_f32_e32 v6, v6
	v_add_u32_e32 v7, s8, v3
	v_mul_f32_e32 v6, 0x4f7ffffe, v6
	v_cvt_u32_f32_e32 v6, v6
	v_mul_lo_u32 v3, v5, v6
	v_mul_hi_u32 v3, v6, v3
	v_add_u32_e32 v3, v6, v3
	v_mul_hi_u32 v3, v7, v3
	v_mul_lo_u32 v5, v3, v4
	v_sub_u32_e32 v5, v7, v5
	v_add_u32_e32 v6, 1, v3
	v_cmp_ge_u32_e32 vcc, v5, v4
	s_nop 1
	v_cndmask_b32_e32 v3, v3, v6, vcc
	v_sub_u32_e32 v6, v5, v4
	v_cndmask_b32_e32 v5, v5, v6, vcc
	v_add_u32_e32 v6, 1, v3
	v_cmp_ge_u32_e32 vcc, v5, v4
	v_add_u32_e32 v5, 1, v7
	s_nop 0
	v_cndmask_b32_e32 v3, v3, v6, vcc
	v_mul_lo_u32 v6, v4, v3
	v_add_u32_e32 v4, v6, v4
	v_cmp_ne_u32_e32 vcc, v5, v4
	s_and_saveexec_b64 s[8:9], vcc
	s_xor_b64 s[8:9], exec, s[8:9]
	s_cbranch_execz .LBB0_1051
	s_waitcnt lgkmcnt(0)
	v_mov_b32_e32 v2, 0x3500
	global_load_dword v2, v2, s[96:97] sc1
	s_add_u32 s12, s96, 0x3500
	s_addc_u32 s13, s97, 0
	s_waitcnt vmcnt(0)
	v_cmp_eq_u32_e32 vcc, v2, v3
	s_and_saveexec_b64 s[10:11], vcc
	s_cbranch_execz .LBB0_1050
	s_mov_b32 s24, 1
	s_mov_b64 s[14:15], 0
	v_mov_b32_e32 v2, 0
	s_branch .LBB0_1041

.LBB0_1166:
	s_or_b64 exec, exec, s[16:17]
	v_cvt_f32_u32_e32 v6, v4
	s_waitcnt vmcnt(0)
	v_readfirstlane_b32 s6, v5
	v_sub_u32_e32 v5, 0, v4
	v_rcp_iflag_f32_e32 v6, v6
	v_add_u32_e32 v7, s6, v3
	v_mul_f32_e32 v6, 0x4f7ffffe, v6
	v_cvt_u32_f32_e32 v6, v6
	v_mul_lo_u32 v3, v5, v6
	v_mul_hi_u32 v3, v6, v3
	v_add_u32_e32 v3, v6, v3
	v_mul_hi_u32 v3, v7, v3
	v_mul_lo_u32 v5, v3, v4
	v_sub_u32_e32 v5, v7, v5
	v_add_u32_e32 v6, 1, v3
	v_cmp_ge_u32_e32 vcc, v5, v4
	s_nop 1
	v_cndmask_b32_e32 v3, v3, v6, vcc
	v_sub_u32_e32 v6, v5, v4
	v_cndmask_b32_e32 v5, v5, v6, vcc
	v_add_u32_e32 v6, 1, v3
	v_cmp_ge_u32_e32 vcc, v5, v4
	v_add_u32_e32 v5, 1, v7
	s_nop 0
	v_cndmask_b32_e32 v3, v3, v6, vcc
	v_mul_lo_u32 v6, v4, v3
	v_add_u32_e32 v4, v6, v4
	v_cmp_ne_u32_e32 vcc, v5, v4
	s_and_saveexec_b64 s[6:7], vcc
	s_xor_b64 s[6:7], exec, s[6:7]
	s_cbranch_execz .LBB0_1180
	s_waitcnt lgkmcnt(0)
	v_mov_b32_e32 v2, 0x3500
	global_load_dword v2, v2, s[96:97] sc1
	s_add_u32 s18, s96, 0x3500
	s_addc_u32 s19, s97, 0
	s_waitcnt vmcnt(0)
	v_cmp_eq_u32_e32 vcc, v2, v3
	s_and_saveexec_b64 s[16:17], vcc
	s_cbranch_execz .LBB0_1179
	s_mov_b32 s30, 1
	s_mov_b64 s[20:21], 0
	v_mov_b32_e32 v2, 0
	s_branch .LBB0_1170

.LBB0_1241:
	s_or_b64 exec, exec, s[18:19]
	v_cvt_f32_u32_e32 v6, v4
	s_waitcnt vmcnt(0)
	v_readfirstlane_b32 s16, v5
	v_sub_u32_e32 v5, 0, v4
	v_rcp_iflag_f32_e32 v6, v6
	v_add_u32_e32 v7, s16, v3
	v_mul_f32_e32 v6, 0x4f7ffffe, v6
	v_cvt_u32_f32_e32 v6, v6
	v_mul_lo_u32 v3, v5, v6
	v_mul_hi_u32 v3, v6, v3
	v_add_u32_e32 v3, v6, v3
	v_mul_hi_u32 v3, v7, v3
	v_mul_lo_u32 v5, v3, v4
	v_sub_u32_e32 v5, v7, v5
	v_add_u32_e32 v6, 1, v3
	v_cmp_ge_u32_e32 vcc, v5, v4
	s_nop 1
	v_cndmask_b32_e32 v3, v3, v6, vcc
	v_sub_u32_e32 v6, v5, v4
	v_cndmask_b32_e32 v5, v5, v6, vcc
	v_add_u32_e32 v6, 1, v3
	v_cmp_ge_u32_e32 vcc, v5, v4
	v_add_u32_e32 v5, 1, v7
	s_nop 0
	v_cndmask_b32_e32 v3, v3, v6, vcc
	v_mul_lo_u32 v6, v4, v3
	v_add_u32_e32 v4, v6, v4
	v_cmp_ne_u32_e32 vcc, v5, v4
	s_and_saveexec_b64 s[16:17], vcc
	s_xor_b64 s[16:17], exec, s[16:17]
	s_cbranch_execz .LBB0_1255
	s_waitcnt lgkmcnt(0)
	v_mov_b32_e32 v2, 0x3500
	global_load_dword v2, v2, s[96:97] sc1
	s_add_u32 s20, s96, 0x3500
	s_addc_u32 s21, s97, 0
	s_waitcnt vmcnt(0)
	v_cmp_eq_u32_e32 vcc, v2, v3
	s_and_saveexec_b64 s[18:19], vcc
	s_cbranch_execz .LBB0_1254
	s_mov_b32 s34, 1
	s_mov_b64 s[22:23], 0
	v_mov_b32_e32 v2, 0
	s_branch .LBB0_1245

.LBB0_1334:
	s_or_b64 exec, exec, s[16:17]
	v_cvt_f32_u32_e32 v6, v4
	s_waitcnt vmcnt(0)
	v_readfirstlane_b32 s14, v5
	v_sub_u32_e32 v5, 0, v4
	v_rcp_iflag_f32_e32 v6, v6
	v_add_u32_e32 v7, s14, v3
	v_mul_f32_e32 v6, 0x4f7ffffe, v6
	v_cvt_u32_f32_e32 v6, v6
	v_mul_lo_u32 v3, v5, v6
	v_mul_hi_u32 v3, v6, v3
	v_add_u32_e32 v3, v6, v3
	v_mul_hi_u32 v3, v7, v3
	v_mul_lo_u32 v5, v3, v4
	v_sub_u32_e32 v5, v7, v5
	v_add_u32_e32 v6, 1, v3
	v_cmp_ge_u32_e32 vcc, v5, v4
	s_nop 1
	v_cndmask_b32_e32 v3, v3, v6, vcc
	v_sub_u32_e32 v6, v5, v4
	v_cndmask_b32_e32 v5, v5, v6, vcc
	v_add_u32_e32 v6, 1, v3
	v_cmp_ge_u32_e32 vcc, v5, v4
	v_add_u32_e32 v5, 1, v7
	s_nop 0
	v_cndmask_b32_e32 v3, v3, v6, vcc
	v_mul_lo_u32 v6, v4, v3
	v_add_u32_e32 v4, v6, v4
	v_cmp_ne_u32_e32 vcc, v5, v4
	s_and_saveexec_b64 s[14:15], vcc
	s_xor_b64 s[14:15], exec, s[14:15]
	s_cbranch_execz .LBB0_1348
	s_waitcnt lgkmcnt(0)
	v_mov_b32_e32 v2, 0x3500
	global_load_dword v2, v2, s[96:97] sc1
	s_add_u32 s20, s96, 0x3500
	s_addc_u32 s21, s97, 0
	s_waitcnt vmcnt(0)
	v_cmp_eq_u32_e32 vcc, v2, v3
	s_and_saveexec_b64 s[16:17], vcc
	s_cbranch_execz .LBB0_1347
	s_mov_b32 s34, 1
	s_mov_b64 s[22:23], 0
	v_mov_b32_e32 v2, 0
	s_branch .LBB0_1338

.LBB0_1413:
	s_or_b64 exec, exec, s[8:9]
	v_cvt_f32_u32_e32 v6, v4
	s_waitcnt vmcnt(0)
	v_readfirstlane_b32 s6, v5
	v_sub_u32_e32 v5, 0, v4
	v_rcp_iflag_f32_e32 v6, v6
	v_add_u32_e32 v7, s6, v3
	v_mul_f32_e32 v6, 0x4f7ffffe, v6
	v_cvt_u32_f32_e32 v6, v6
	v_mul_lo_u32 v3, v5, v6
	v_mul_hi_u32 v3, v6, v3
	v_add_u32_e32 v3, v6, v3
	v_mul_hi_u32 v3, v7, v3
	v_mul_lo_u32 v5, v3, v4
	v_sub_u32_e32 v5, v7, v5
	v_add_u32_e32 v6, 1, v3
	v_cmp_ge_u32_e32 vcc, v5, v4
	s_nop 1
	v_cndmask_b32_e32 v3, v3, v6, vcc
	v_sub_u32_e32 v6, v5, v4
	v_cndmask_b32_e32 v5, v5, v6, vcc
	v_add_u32_e32 v6, 1, v3
	v_cmp_ge_u32_e32 vcc, v5, v4
	v_add_u32_e32 v5, 1, v7
	s_nop 0
	v_cndmask_b32_e32 v3, v3, v6, vcc
	v_mul_lo_u32 v6, v4, v3
	v_add_u32_e32 v4, v6, v4
	v_cmp_ne_u32_e32 vcc, v5, v4
	s_and_saveexec_b64 s[6:7], vcc
	s_xor_b64 s[6:7], exec, s[6:7]
	s_cbranch_execz .LBB0_1427
	s_waitcnt lgkmcnt(0)
	v_mov_b32_e32 v2, 0x3500
	global_load_dword v2, v2, s[96:97] sc1
	s_add_u32 s10, s96, 0x3500
	s_addc_u32 s11, s97, 0
	s_waitcnt vmcnt(0)
	v_cmp_eq_u32_e32 vcc, v2, v3
	s_and_saveexec_b64 s[8:9], vcc
	s_cbranch_execz .LBB0_1426
	s_mov_b32 s22, 1
	s_mov_b64 s[12:13], 0
	v_mov_b32_e32 v2, 0
	s_branch .LBB0_1417
